# block roles remapped: scan blocks are the even local block indices below 32 of each XCD instead of local indices 0..15
# speedup vs baseline: 1.0073x; 1.0053x over previous
_Z4megaILb1EEv6Paramsiii:
	s_load_dwordx8 s[92:99], s[0:1], 0x100
	v_and_b32_e32 v175, 0x3ff, v0
	s_lshr_b32 s4, s2, 3
	s_and_b32 s2, s2, 7
	s_and_b32 s5, s4, 1
	s_lshl_b32 s5, s5, 5
	s_lshr_b32 s4, s4, 1
	s_or_b32 s4, s4, s5
	s_lshl_b32 s4, s4, 3
	s_or_b32 s2, s2, s4
	s_nop 0
	v_writelane_b32 v253, s2, 0
	v_cmp_eq_u32_e64 s[4:5], 0, v175
	s_mov_b64 s[2:3], exec
	s_nop 0
	v_writelane_b32 v253, s4, 1
	s_nop 1
	v_writelane_b32 v253, s5, 2
	s_and_b64 s[4:5], s[2:3], s[4:5]
	s_mov_b64 exec, s[4:5]
	s_cbranch_execz .LBB0_2
	s_mov_b64 s[4:5], src_shared_base
	v_mov_b32_e32 v2, 0x10010
	v_mov_b32_e32 v3, s5
	v_mov_b32_e32 v1, 0
	flat_store_dword v[2:3], v1 sc0 sc1
	s_waitcnt vmcnt(0)
	v_mov_b32_e32 v2, 0x10014
	flat_store_dword v[2:3], v1 sc0 sc1
	s_waitcnt vmcnt(0)
